# P3 attention: softmax reference only advanced when a row max moves by more than 8 log2 units; otherwise alpha=1 and the 32 accumulator-rescale multiplies are skipped (f32 accumulate unchanged)
# baseline (speedup 1.0000x reference)
; #define MFMA32(a, b, c) __builtin_amdgcn_mfma_f32_32x32x16_bf16((a), (b), (c), 0, 0, 0)
; #define ATT_LDK(buf, g) do { _Pragma("unroll") for (int kk = 0; kk < 2; ++kk) { \
;                 ka[buf][kk][0] = *(const LAS bf16x8*)(Kb + r * KSTR + (2 * (g) + kk) * 32 + hh * 16); ka[buf][kk][1] = *(const LAS bf16x8*)(Kb + (32 + r) * KSTR + (2 * (g) + kk) * 32 + hh * 16); } } while (0)
; #define ATT_LDV(buf, d) do { _Pragma("unroll") for (int kb = 0; kb < 2; ++kb) _Pragma("unroll") for (int s = 0; s < 2; ++s) { \
;                 const LAS unsigned char* p_ = Vb + vlane + (32 * kb + 16 * s) * VSTR + (d) * 64; vl[buf][2 * kb + s] = trread(p_); vh[buf][2 * kb + s] = trread(p_ + 8 * VSTR); } } while (0)
; template <int NKS, bool ALLIN = false> ...
;     ...
; #pragma unroll
;             for (int i = 0; i < 16; ++i) { s0[i] = 0.f; s1[i] = 0.f; }
;             bf16x8 ka[2][2][2];
;     ...
;             ATT_LDK(0, 0); ATT_LDK(1, 1);
;             __builtin_amdgcn_sched_barrier(0);
; #pragma unroll
;             for (int g = 0; g < NKS / 2; ++g) {
; #pragma unroll
;                 for (int kk = 0; kk < 2; ++kk) { s0 = MFMA32(ka[g & 1][kk][0], qf[2 * g + kk], s0); s1 = MFMA32(ka[g & 1][kk][1], qf[2 * g + kk], s1); }
;                 __builtin_amdgcn_sched_barrier(0);
;                 if (g + 2 < NKS / 2) { ATT_LDK(g & 1, g + 2); __builtin_amdgcn_sched_barrier(0); }
;             }
;     ...
;             s16x4 vl[2][4], vh[2][4];
;     ...
;             ATT_LDV(0, 0); ATT_LDV(1, 1);
;             __builtin_amdgcn_sched_barrier(0);
;             float mx = -INFINITY;
; #pragma unroll
;             for (int i = 0; i < 16; ++i) mx = fmaxf(mx, fmaxf(s0[i], s1[i]));
;             mx = fmaxf(mx, __shfl_xor(mx, 32)) * c2;
;             const float mnew = fmaxf(mrun, mx), alpha = __builtin_amdgcn_exp2f(mrun - mnew); mrun = mnew;
.LBB0_108:
	s_and_b32 s19, s22, 1
	s_mul_i32 s22, s19, 0x6400
	v_add_u32_e32 v0, s22, v215
	ds_read_b128 v[2:5], v0
	ds_read_b128 v[6:9], v0 offset:32
	ds_read_b128 v[10:13], v0 offset:12800
	ds_read_b128 v[180:183], v0 offset:12832
	ds_read_b128 v[184:187], v0 offset:64
	ds_read_b128 v[188:191], v0 offset:96
	ds_read_b128 v[192:195], v0 offset:12864
	ds_read_b128 v[196:199], v0 offset:12896
	s_mulk_i32 s19, 0x5000
	s_waitcnt lgkmcnt(7)
	v_mfma_f32_32x32x16_bf16 v[96:111], v[2:5], v[132:135], 0
	s_waitcnt lgkmcnt(5)
	v_mfma_f32_32x32x16_bf16 v[80:95], v[10:13], v[132:135], 0
	v_mfma_f32_32x32x16_bf16 v[96:111], v[6:9], v[136:139], v[96:111]
	s_waitcnt lgkmcnt(4)
	v_mfma_f32_32x32x16_bf16 v[80:95], v[180:183], v[136:139], v[80:95]
	ds_read_b128 v[2:5], v0 offset:128
	ds_read_b128 v[6:9], v0 offset:160
	ds_read_b128 v[10:13], v0 offset:12928
	ds_read_b128 v[180:183], v0 offset:12960
	s_waitcnt lgkmcnt(7)
	v_mfma_f32_32x32x16_bf16 v[96:111], v[184:187], v[140:143], v[96:111]
	s_waitcnt lgkmcnt(5)
	v_mfma_f32_32x32x16_bf16 v[80:95], v[192:195], v[140:143], v[80:95]
	v_mfma_f32_32x32x16_bf16 v[96:111], v[188:191], v[144:147], v[96:111]
	s_waitcnt lgkmcnt(4)
	v_mfma_f32_32x32x16_bf16 v[80:95], v[196:199], v[144:147], v[80:95]
	ds_read_b128 v[184:187], v0 offset:192
	ds_read_b128 v[188:191], v0 offset:224
	ds_read_b128 v[192:195], v0 offset:12992
	ds_read_b128 v[196:199], v0 offset:13024
	s_waitcnt lgkmcnt(7)
	v_mfma_f32_32x32x16_bf16 v[96:111], v[2:5], v[148:151], v[96:111]
	s_waitcnt lgkmcnt(5)
	v_mfma_f32_32x32x16_bf16 v[80:95], v[10:13], v[148:151], v[80:95]
	v_mfma_f32_32x32x16_bf16 v[96:111], v[6:9], v[152:155], v[96:111]
	s_waitcnt lgkmcnt(4)
	v_mfma_f32_32x32x16_bf16 v[80:95], v[180:183], v[152:155], v[80:95]
	ds_read_b128 v[2:5], v0 offset:256
	ds_read_b128 v[6:9], v0 offset:288
	ds_read_b128 v[10:13], v0 offset:13056
	ds_read_b128 v[180:183], v0 offset:13088
	s_waitcnt lgkmcnt(7)
	v_mfma_f32_32x32x16_bf16 v[96:111], v[184:187], v[156:159], v[96:111]
	s_waitcnt lgkmcnt(5)
	v_mfma_f32_32x32x16_bf16 v[80:95], v[192:195], v[156:159], v[80:95]
	v_mfma_f32_32x32x16_bf16 v[96:111], v[188:191], v[160:163], v[96:111]
	s_waitcnt lgkmcnt(4)
	v_mfma_f32_32x32x16_bf16 v[80:95], v[196:199], v[160:163], v[80:95]
	ds_read_b128 v[184:187], v0 offset:320
	ds_read_b128 v[188:191], v0 offset:352
	ds_read_b128 v[192:195], v0 offset:13120
	ds_read_b128 v[196:199], v0 offset:13152
	s_waitcnt lgkmcnt(7)
	v_mfma_f32_32x32x16_bf16 v[96:111], v[2:5], v[164:167], v[96:111]
	s_waitcnt lgkmcnt(5)
	v_mfma_f32_32x32x16_bf16 v[80:95], v[10:13], v[164:167], v[80:95]
	v_mfma_f32_32x32x16_bf16 v[96:111], v[6:9], v[168:171], v[96:111]
	s_waitcnt lgkmcnt(4)
	v_mfma_f32_32x32x16_bf16 v[80:95], v[180:183], v[168:171], v[80:95]
	s_waitcnt lgkmcnt(3)
	v_mfma_f32_32x32x16_bf16 v[96:111], v[184:187], v[172:175], v[96:111]
	s_waitcnt lgkmcnt(1)
	v_mfma_f32_32x32x16_bf16 v[80:95], v[192:195], v[172:175], v[80:95]
	v_mfma_f32_32x32x16_bf16 v[96:111], v[188:191], v[176:179], v[96:111]
	s_waitcnt lgkmcnt(0)
	v_mfma_f32_32x32x16_bf16 v[80:95], v[196:199], v[176:179], v[80:95]
	v_add_u32_e32 v222, s19, v213
	v_add_u32_e32 v218, 0xc800, v222
	ds_read_b64_tr_b16 v[184:185], v222 offset:51200
	ds_read_b64_tr_b16 v[186:187], v222 offset:53760
	ds_read_b64_tr_b16 v[182:183], v222 offset:53824
	ds_read_b64_tr_b16 v[180:181], v222 offset:51264
	ds_read_b64_tr_b16 v[196:197], v222 offset:56320
	ds_read_b64_tr_b16 v[198:199], v222 offset:58880
	ds_read_b64_tr_b16 v[12:13], v222 offset:58944
	ds_read_b64_tr_b16 v[10:11], v222 offset:56384
	ds_read_b64_tr_b16 v[192:193], v222 offset:61440
	ds_read_b64_tr_b16 v[194:195], v222 offset:64000
	ds_read_b64_tr_b16 v[8:9], v222 offset:64064
	ds_read_b64_tr_b16 v[6:7], v222 offset:61504
	ds_read_b64_tr_b16 v[188:189], v218 offset:15360
	ds_read_b64_tr_b16 v[190:191], v218 offset:17920
	ds_read_b64_tr_b16 v[4:5], v218 offset:17984
	ds_read_b64_tr_b16 v[2:3], v218 offset:15424
	v_max_f32_e32 v0, v80, v80
	v_max_f32_e32 v14, v96, v96
	v_max_f32_e32 v0, v14, v0
	v_max_f32_e32 v14, v81, v81
	v_max_f32_e32 v15, v97, v97
	v_max_f32_e32 v14, v15, v14
	v_max3_f32 v0, v0, s73, v14
	v_max_f32_e32 v14, v82, v82
	v_max_f32_e32 v15, v98, v98
	v_max_f32_e32 v14, v15, v14
	v_max_f32_e32 v15, v83, v83
	v_max_f32_e32 v223, v99, v99
	v_max_f32_e32 v15, v223, v15
	v_max3_f32 v0, v0, v14, v15
	v_max_f32_e32 v14, v84, v84
	v_max_f32_e32 v15, v100, v100
	v_max_f32_e32 v14, v15, v14
	v_max_f32_e32 v15, v85, v85
	v_max_f32_e32 v223, v101, v101
	v_max_f32_e32 v15, v223, v15
	v_max3_f32 v0, v0, v14, v15
	v_max_f32_e32 v14, v86, v86
	v_max_f32_e32 v15, v102, v102
	v_max_f32_e32 v14, v15, v14
	v_max_f32_e32 v15, v87, v87
	v_max_f32_e32 v223, v103, v103
	v_max_f32_e32 v15, v223, v15
	v_max3_f32 v0, v0, v14, v15
	v_max_f32_e32 v14, v88, v88
	v_max_f32_e32 v15, v104, v104
	v_max_f32_e32 v14, v15, v14
	v_max_f32_e32 v15, v89, v89
	v_max_f32_e32 v223, v105, v105
	v_max_f32_e32 v15, v223, v15
	v_max3_f32 v0, v0, v14, v15
	v_max_f32_e32 v14, v90, v90
	v_max_f32_e32 v15, v106, v106
	v_max_f32_e32 v14, v15, v14
	v_max_f32_e32 v15, v91, v91
	v_max_f32_e32 v223, v107, v107
	v_max_f32_e32 v15, v223, v15
	v_max3_f32 v0, v0, v14, v15
	v_max_f32_e32 v14, v92, v92
	v_max_f32_e32 v15, v108, v108
	v_max_f32_e32 v14, v15, v14
	v_max_f32_e32 v15, v93, v93
	v_max_f32_e32 v223, v109, v109
	v_max_f32_e32 v15, v223, v15
	v_max3_f32 v0, v0, v14, v15
	v_max_f32_e32 v14, v94, v94
	v_max_f32_e32 v15, v110, v110
	v_max_f32_e32 v14, v15, v14
	v_max_f32_e32 v15, v95, v95
	v_max_f32_e32 v223, v111, v111
	v_max_f32_e32 v15, v223, v15
	v_max3_f32 v0, v0, v14, v15
	v_and_b32_e32 v15, 64, v220
	v_xor_b32_e32 v14, 32, v220
	v_add_u32_e32 v15, 64, v15
	v_cmp_lt_i32_e32 vcc, v14, v15
	s_nop 1
	v_cndmask_b32_e32 v14, v220, v14, vcc
	v_lshlrev_b32_e32 v14, 2, v14
	ds_bpermute_b32 v14, v14, v0
	s_waitcnt lgkmcnt(0)
	v_max_f32_e32 v14, v14, v14
	v_max_f32_e32 v0, v0, v14
	v_mul_f32_e32 v0, 0x3dd53b94, v0
	v_max_f32_e32 v14, v219, v219
	v_max_f32_e32 v223, v14, v0
	v_sub_f32_e32 v15, v223, v14
	v_cmp_lt_f32_e32 vcc, 0x41000000, v15
	s_cbranch_vccnz .Latt_upd
	v_mov_b32_e32 v223, v14
; template <int NKS, bool ALLIN = false> ...
;     ...
;             const float mnew = fmaxf(mrun, mx), alpha = __builtin_amdgcn_exp2f(mrun - mnew); mrun = mnew;
;             float ls = 0.f;
; #pragma unroll
;             for (int i = 0; i < 16; ++i) { s0[i] = __builtin_amdgcn_exp2f(fmaf(s0[i], c2, -mnew)); s1[i] = __builtin_amdgcn_exp2f(fmaf(s1[i], c2, -mnew)); ls += s0[i] + s1[i]; }
;             lrun = lrun * alpha + ls;
; #pragma unroll
;             for (int d = 0; d < 4; ++d)
; #pragma unroll
;                 for (int i = 0; i < 16; ++i) o[d][i] *= alpha;
;             bf16x8 pf[4];
;             pf[0] = packacc8(s0, 0); pf[1] = packacc8(s0, 8); pf[2] = packacc8(s1, 0); pf[3] = packacc8(s1, 8);
.Latt_upd:
	v_fma_f32 v14, v98, s80, -v223
	v_exp_f32_e32 v234, v14
	v_fma_f32 v14, v82, s80, -v223
	v_fma_f32 v0, v96, s80, -v223
	v_exp_f32_e32 v235, v14
	v_fma_f32 v14, v99, s80, -v223
	v_exp_f32_e32 v224, v0
	v_fma_f32 v0, v80, s80, -v223
	v_exp_f32_e32 v236, v14
	v_fma_f32 v14, v83, s80, -v223
	v_exp_f32_e32 v225, v0
	v_fma_f32 v0, v97, s80, -v223
	v_exp_f32_e32 v237, v14
	v_fma_f32 v14, v100, s80, -v223
	v_exp_f32_e32 v226, v0
	v_fma_f32 v0, v81, s80, -v223
	v_exp_f32_e32 v81, v14
	v_fma_f32 v14, v84, s80, -v223
	v_exp_f32_e32 v15, v14
	v_fma_f32 v14, v101, s80, -v223
	v_fma_f32 v82, v102, s80, -v223
	v_exp_f32_e32 v80, v14
	v_fma_f32 v14, v85, s80, -v223
	v_exp_f32_e32 v85, v82
	v_fma_f32 v82, v86, s80, -v223
	v_fma_f32 v86, v104, s80, -v223
	v_exp_f32_e32 v101, v86
	v_fma_f32 v86, v88, s80, -v223
	v_fma_f32 v88, v106, s80, -v223
	v_exp_f32_e32 v83, v82
	v_fma_f32 v82, v103, s80, -v223
	v_exp_f32_e32 v103, v88
	v_fma_f32 v88, v90, s80, -v223
	v_exp_f32_e32 v84, v82
	v_fma_f32 v82, v87, s80, -v223
	v_exp_f32_e32 v87, v86
	v_fma_f32 v86, v105, s80, -v223
	v_exp_f32_e32 v105, v88
	v_fma_f32 v88, v107, s80, -v223
	v_exp_f32_e32 v102, v88
	v_fma_f32 v88, v91, s80, -v223
	v_exp_f32_e32 v227, v0
	v_exp_f32_e32 v104, v88
	v_fma_f32 v88, v108, s80, -v223
	v_exp_f32_e32 v107, v88
	v_fma_f32 v88, v92, s80, -v223
	v_exp_f32_e32 v231, v88
	v_fma_f32 v88, v109, s80, -v223
	v_sub_f32_e32 v0, v219, v223
	v_add_f32_e32 v219, v224, v225
	v_exp_f32_e32 v14, v14
	v_exp_f32_e32 v106, v88
	v_fma_f32 v88, v93, s80, -v223
	v_add_f32_e32 v229, v226, v227
	v_exp_f32_e32 v230, v88
	v_fma_f32 v88, v110, s80, -v223
	v_add_f32_e32 v110, 0, v219
	v_exp_f32_e32 v82, v82
	v_add_f32_e32 v238, v234, v235
	v_add_f32_e32 v110, v229, v110
	v_add_f32_e32 v239, v236, v237
	v_exp_f32_e32 v100, v86
	v_fma_f32 v86, v89, s80, -v223
	v_add_f32_e32 v110, v238, v110
	v_pk_add_f32 v[96:97], v[80:81], v[14:15]
	v_exp_f32_e32 v86, v86
	v_add_f32_e32 v110, v239, v110
	v_exp_f32_e32 v109, v88
	v_fma_f32 v88, v94, s80, -v223
	v_add_f32_e32 v97, v97, v110
	v_pk_add_f32 v[98:99], v[84:85], v[82:83]
	v_exp_f32_e32 v233, v88
	v_fma_f32 v88, v111, s80, -v223
	v_add_f32_e32 v96, v96, v97
	v_exp_f32_e32 v108, v88
	v_fma_f32 v88, v95, s80, -v223
	v_add_f32_e32 v96, v99, v96
	v_exp_f32_e32 v232, v88
	v_pk_add_f32 v[88:89], v[100:101], v[86:87]
	v_add_f32_e32 v96, v98, v96
	v_add_f32_e32 v89, v89, v96
	v_pk_add_f32 v[90:91], v[102:103], v[104:105]
	v_add_f32_e32 v88, v88, v89
	v_add_f32_e32 v88, v91, v88
	v_exp_f32_e32 v0, v0
	v_pk_add_f32 v[92:93], v[106:107], v[230:231]
	v_add_f32_e32 v88, v90, v88
	v_add_f32_e32 v88, v93, v88
	v_pk_add_f32 v[94:95], v[108:109], v[232:233]
	v_add_f32_e32 v88, v92, v88
	v_add_f32_e32 v88, v95, v88
	v_cmp_neq_f32_e32 vcc, 1.0, v0
	s_cbranch_vccz .Latt_noscale
	v_pk_mul_f32 v[78:79], v[78:79], v[0:1] op_sel_hi:[1,0]
	v_pk_mul_f32 v[76:77], v[76:77], v[0:1] op_sel_hi:[1,0]
	v_pk_mul_f32 v[74:75], v[74:75], v[0:1] op_sel_hi:[1,0]
	v_pk_mul_f32 v[72:73], v[72:73], v[0:1] op_sel_hi:[1,0]
	v_pk_mul_f32 v[70:71], v[70:71], v[0:1] op_sel_hi:[1,0]
	v_pk_mul_f32 v[68:69], v[68:69], v[0:1] op_sel_hi:[1,0]
	v_pk_mul_f32 v[66:67], v[66:67], v[0:1] op_sel_hi:[1,0]
	v_pk_mul_f32 v[64:65], v[64:65], v[0:1] op_sel_hi:[1,0]
	v_pk_mul_f32 v[62:63], v[62:63], v[0:1] op_sel_hi:[1,0]
	v_pk_mul_f32 v[60:61], v[60:61], v[0:1] op_sel_hi:[1,0]
	v_pk_mul_f32 v[58:59], v[58:59], v[0:1] op_sel_hi:[1,0]
	v_pk_mul_f32 v[56:57], v[56:57], v[0:1] op_sel_hi:[1,0]
	v_pk_mul_f32 v[54:55], v[54:55], v[0:1] op_sel_hi:[1,0]
	v_pk_mul_f32 v[52:53], v[52:53], v[0:1] op_sel_hi:[1,0]
	v_pk_mul_f32 v[50:51], v[50:51], v[0:1] op_sel_hi:[1,0]
	v_pk_mul_f32 v[48:49], v[48:49], v[0:1] op_sel_hi:[1,0]
	v_pk_mul_f32 v[46:47], v[46:47], v[0:1] op_sel_hi:[1,0]
	v_pk_mul_f32 v[44:45], v[44:45], v[0:1] op_sel_hi:[1,0]
	v_pk_mul_f32 v[42:43], v[42:43], v[0:1] op_sel_hi:[1,0]
	v_pk_mul_f32 v[40:41], v[40:41], v[0:1] op_sel_hi:[1,0]
	v_pk_mul_f32 v[38:39], v[38:39], v[0:1] op_sel_hi:[1,0]
	v_pk_mul_f32 v[36:37], v[36:37], v[0:1] op_sel_hi:[1,0]
	v_pk_mul_f32 v[34:35], v[34:35], v[0:1] op_sel_hi:[1,0]
	v_pk_mul_f32 v[32:33], v[32:33], v[0:1] op_sel_hi:[1,0]
	v_pk_mul_f32 v[30:31], v[30:31], v[0:1] op_sel_hi:[1,0]
	v_pk_mul_f32 v[28:29], v[28:29], v[0:1] op_sel_hi:[1,0]
	v_pk_mul_f32 v[26:27], v[26:27], v[0:1] op_sel_hi:[1,0]
	v_pk_mul_f32 v[24:25], v[24:25], v[0:1] op_sel_hi:[1,0]
	v_pk_mul_f32 v[22:23], v[22:23], v[0:1] op_sel_hi:[1,0]
	v_pk_mul_f32 v[20:21], v[20:21], v[0:1] op_sel_hi:[1,0]
	v_pk_mul_f32 v[18:19], v[18:19], v[0:1] op_sel_hi:[1,0]
	v_pk_mul_f32 v[16:17], v[16:17], v[0:1] op_sel_hi:[1,0]
	s_nop 0
	s_nop 0
	s_nop 0
	s_nop 0
	s_nop 0
	s_nop 0
	s_nop 0
	s_nop 0
	s_nop 0
.Latt_noscale:
	v_add_f32_e32 v219, v94, v88
	v_cvt_pk_bf16_f32 v88, v224, v226
	v_cvt_pk_bf16_f32 v89, v234, v236
	v_cvt_pk_bf16_f32 v90, v81, v80
	v_cvt_pk_bf16_f32 v91, v85, v84
	v_cvt_pk_bf16_f32 v92, v101, v100
	v_cvt_pk_bf16_f32 v93, v103, v102
	v_cvt_pk_bf16_f32 v94, v107, v106
	v_cvt_pk_bf16_f32 v95, v109, v108
	v_cvt_pk_bf16_f32 v96, v225, v227
	v_cvt_pk_bf16_f32 v97, v235, v237
	v_cvt_pk_bf16_f32 v98, v15, v14
	v_cvt_pk_bf16_f32 v99, v83, v82
	v_cvt_pk_bf16_f32 v80, v87, v86
	v_cvt_pk_bf16_f32 v81, v105, v104
	v_cvt_pk_bf16_f32 v82, v231, v230
	v_cvt_pk_bf16_f32 v83, v233, v232
	s_andn2_b64 vcc, exec, s[16:17]
	s_cbranch_vccnz .Latt_st_skip
	s_and_b32 s19, s18, 1
	s_mul_i32 s23, s19, 0x6400
	v_add3_u32 v240, s23, v205, v202
	s_mulk_i32 s19, 0xec00
	s_waitcnt vmcnt(4)
	ds_write_b128 v240, v[112:115]
	v_add3_u32 v240, s23, v216, v202
	s_add_i32 s19, s23, s19
	s_waitcnt vmcnt(3)
	ds_write_b128 v240, v[116:119]
	v_add3_u32 v240, s23, v211, v204
	s_waitcnt vmcnt(2)
	ds_write_b128 v240, v[120:123] offset:256
	v_add3_u32 v240, s19, v212, v202
	s_waitcnt vmcnt(1)
	ds_write_b128 v240, v[124:127] offset:51200
	v_add3_u32 v240, s19, v217, v202
	s_waitcnt vmcnt(0)
	ds_write_b128 v240, v[128:131] offset:51200

; __global__ void __launch_bounds__(512, 2) mk_fwd(Args a_) {
;     ...
;             for (int ui = bid; ui < 1024 && !(MK_DUPS == 3 && rep == 1); ui += G) {
;                 const int rnd = ui >> 8, c0 = ui & 255, xcd = c0 & 7, w = c0 >> 3;
;                 const int bh = 8 * xcd + 2 * rnd + (w >> 4), b = bh >> 4, h = bh & 15, qb = (rnd & 1) ? 15 - (w & 15) : (w & 15);
;                 const size_t row0 = (size_t)b * SEQL + qb * 256, kr0 = (size_t)b * SEQL;
;                 attn_unit<12>(lds, tid, qn + row0 * 2048 + h * 128, 2048, qpe + row0 * 1024 + h * 64, 1024, kn + kr0 * 2048 + h * 128, 2048, kpe + kr0 * 64, 64,
;                               vb + kr0 * 2048 + h * 128, 2048, ya + row0 * 2048 + h * 128, 2048, 4 * qb + 4, 4 * qb + (wid >> 1) + 1, 0.07216878364870322f * 1.4426950408889634f);
;             }
;             for (int ui = bid; ui < 1024; ui += G) mlstm_pre_unit(lds, tid, ui, z1, ws, MK_DUPS != 3 || rep == 1);
.LBB0_109:
	s_mov_b32 s8, s34
	s_branch .LBB0_111
	s_nop 0
	s_nop 0
	s_nop 0
	s_nop 0
	s_nop 0
	s_nop 0
	s_nop 0
	s_nop 0
	s_nop 0
	s_nop 0
	s_nop 0
	s_nop 0
	s_nop 0
	s_nop 0
	s_nop 0
	s_nop 0
	s_nop 0
	s_nop 0
	s_nop 0
	s_nop 0
	s_nop 0
	s_nop 0
	s_nop 0
	s_nop 0
	s_nop 0
	s_nop 0
	s_nop 0
	s_nop 0
	s_nop 0
	s_nop 0
	s_nop 0
	s_nop 0
	s_nop 0
	s_nop 0
	s_nop 0
	s_nop 0
	s_nop 0
	s_nop 0
	s_nop 0
	s_nop 0
	s_nop 0
	s_nop 0
	s_nop 0
	s_nop 0
	s_nop 0
	s_nop 0
	s_nop 0
	s_nop 0
	s_nop 0
	s_nop 0
	s_nop 0
	s_nop 0
	s_nop 0
	s_nop 0
	s_nop 0
	s_nop 0
	s_nop 0
	s_nop 0
	s_nop 0
	s_nop 0
	s_nop 0
	s_nop 0
	s_nop 0
	s_nop 0
	s_nop 0
	s_nop 0
	s_nop 0
	s_nop 0
	s_nop 0
	s_nop 0
	s_nop 0
	s_nop 0
	s_nop 0
	s_nop 0
	s_nop 0
	s_nop 0
	s_nop 0
	s_nop 0
	s_nop 0
	s_nop 0
	s_nop 0
	s_nop 0
	s_nop 0
	s_nop 0
	s_nop 0
	s_nop 0
	s_nop 0
	s_nop 0
	s_nop 0
	s_nop 0
	s_nop 0
	s_nop 0
	s_nop 0
	s_nop 0
	s_nop 0
	s_nop 0
	s_nop 0
	s_nop 0
	s_nop 0
	s_nop 0
	s_nop 0
	s_nop 0
	s_nop 0
	s_nop 0
	s_nop 0
	s_nop 0
	s_nop 0
	s_nop 0
	s_nop 0
	s_nop 0
	s_nop 0
	s_nop 0
	s_nop 0
	s_nop 0
	s_nop 0
	s_nop 0
	s_nop 0
	s_nop 0
	s_nop 0
	s_nop 0
	s_nop 0
	s_nop 0
	s_nop 0
	s_nop 0
	s_nop 0
	s_nop 0
	s_nop 0
	s_nop 0
	s_nop 0
	s_nop 0
	s_nop 0
	s_nop 0
	s_nop 0
	s_nop 0
	s_nop 0
	s_nop 0
	s_nop 0
	s_nop 0
	s_nop 0
	s_nop 0
	s_nop 0
	s_nop 0
	s_nop 0
	s_nop 0
	s_nop 0
	s_nop 0
	s_nop 0
	s_nop 0
	s_nop 0
	s_nop 0
	s_nop 0
	s_nop 0
	s_nop 0
	s_nop 0
	s_nop 0
	s_nop 0
	s_nop 0
	s_nop 0
	s_nop 0
	s_nop 0
	s_nop 0
	s_nop 0
	s_nop 0
	s_nop 0
	s_nop 0
	s_nop 0
	s_nop 0
	s_nop 0
	s_nop 0
	s_nop 0
	s_nop 0
	s_nop 0
	s_nop 0
	s_nop 0
	s_nop 0
	s_nop 0
	s_nop 0
	s_nop 0
	s_nop 0
	s_nop 0
	s_nop 0
	s_nop 0
	s_nop 0
	s_nop 0
	s_nop 0
	s_nop 0
	s_nop 0
	s_nop 0
	s_nop 0
	s_nop 0
	s_nop 0
	s_nop 0
	s_nop 0
	s_nop 0
	s_nop 0
	s_nop 0
	s_nop 0
	s_nop 0
	s_nop 0
	s_nop 0
	s_nop 0
	s_nop 0
	s_nop 0
	s_nop 0
	s_nop 0
	s_nop 0
	s_nop 0
	s_nop 0
	s_nop 0
	s_nop 0
	s_nop 0
	s_nop 0
	s_nop 0
	s_nop 0
	s_nop 0
	s_nop 0
	s_nop 0
	s_nop 0
	s_nop 0
	s_nop 0
	s_nop 0
	s_nop 0
	s_nop 0
	s_nop 0
	s_nop 0
	s_nop 0
	s_nop 0
	s_nop 0
	s_nop 0
	s_nop 0
	s_nop 0
	s_nop 0
	s_nop 0
	s_nop 0
	s_nop 0
	s_nop 0
	s_nop 0
	s_nop 0
	s_nop 0
	s_nop 0
	s_nop 0
	s_nop 0
	s_nop 0
	s_nop 0
	s_nop 0
	s_nop 0
	s_nop 0
	s_nop 0
	s_nop 0
	s_nop 0
	s_nop 0
	s_nop 0
	s_nop 0
	s_nop 0
	s_nop 0
	s_nop 0
	s_nop 0
	s_nop 0
	s_nop 0
	s_nop 0
	s_nop 0
	s_nop 0
	s_nop 0
	s_nop 0
	s_nop 0
	s_nop 0
	s_nop 0
	s_nop 0
	s_nop 0
	s_nop 0
	s_nop 0
	s_nop 0
	s_nop 0
	s_nop 0
	s_nop 0
	s_nop 0
	s_nop 0
	s_nop 0
	s_nop 0
	s_nop 0
	s_nop 0
	s_nop 0
	s_nop 0
	s_nop 0
	s_nop 0
	s_nop 0
	s_nop 0
	s_nop 0
	s_nop 0
	s_nop 0
	s_nop 0
	s_nop 0
	s_nop 0
	s_nop 0
	s_nop 0
	s_nop 0
	s_nop 0
	s_nop 0
	s_nop 0
	s_nop 0
	s_nop 0
	s_nop 0
	s_nop 0
	s_nop 0
	s_nop 0
	s_nop 0
	s_nop 0
	s_nop 0
	s_nop 0
	s_nop 0
	s_nop 0
	s_nop 0
	s_nop 0
	s_nop 0
	s_nop 0
	s_nop 0
	s_nop 0
	s_nop 0
	s_nop 0
	s_nop 0
	s_nop 0
	s_nop 0
	s_nop 0
	s_nop 0
	s_nop 0
	s_nop 0
	s_nop 0
	s_nop 0
	s_nop 0
	s_nop 0
	s_nop 0
	s_nop 0
	s_nop 0
	s_nop 0
	s_nop 0
	s_nop 0
	s_nop 0
	s_nop 0
	s_nop 0
	s_nop 0
	s_nop 0
	s_nop 0
	s_nop 0
	s_nop 0
	s_nop 0
	s_nop 0
	s_nop 0
	s_nop 0
	s_nop 0
	s_nop 0
	s_nop 0
	s_nop 0
	s_nop 0
.LBB0_110:
	s_or_b64 exec, exec, s[16:17]
	s_add_i32 s8, s8, s56
	s_cmpk_gt_i32 s8, 0x3ff
	s_barrier
	s_cbranch_scc1 .LBB0_219
